# v15 + LN loop: register prefetch of the next iteration's z16 rows (guarded by loop bound), copy instead of load at the next top
# speedup vs baseline: 1.0099x; 1.0013x over previous
; template <int NR>
; __device__ __forceinline__ void ln_rows(const _Float16* z, bf16* xb, float* st, float* outf, int m0, int stride, const float* g, const float* b, int lane, bool final_out) {
;     ...
;         f32x4* xr = (f32x4*)(outf + (size_t)m * D) + lane; unsigned long long* o8 = (unsigned long long*)(xb + (size_t)m * D) + lane;
; #pragma unroll
;         for (int j = 0; j < 4; ++j) { const f32x4 gg = ((const f32x4*)g)[lane + 64 * j], bb = ((const f32x4*)b)[lane + 64 * j];
; __global__ void __launch_bounds__(NTHR, 2) fwd_kernel(Params p) {
;     ...
;             const int li = (k == 2) ? 0 : (k == 9 ? 1 : 2);
;             const float* gg = p.ln_g + (size_t)(L * 3 + li) * D; const float* bb = p.ln_b + (size_t)(L * 3 + li) * D;
;             const bool wbf = !(L == 1 && k == 12);
;             { int m = gw;
;               for (; m + 3 * ngw < T; m += 4 * ngw) ln_rows<4>((const _Float16*)(ws_ + WS_Z16), XB, (float*)(ws_ + WS_STATS), p.out, m, ngw, gg, bb, lane, !wbf);
.LBB0_627:
	s_nop 0
	v_readlane_b32 s0, v254, 51
	v_readlane_b32 s1, v254, 52
	s_and_b64 vcc, exec, s[0:1]
	s_cbranch_vccz .LBB0_765
	v_readlane_b32 s0, v254, 50
	s_cmp_eq_u32 s0, 12
	v_readlane_b32 s0, v254, 45
	s_mul_i32 s0, s0, 3
	v_readlane_b32 s1, v254, 53
	s_cselect_b64 s[6:7], -1, 0
	s_add_i32 s0, s1, s0
	s_ashr_i32 s1, s0, 31
	v_readlane_b32 s16, v253, 56
	s_lshl_b64 s[0:1], s[0:1], 12
	v_readlane_b32 s26, v254, 2
	v_readlane_b32 s27, v254, 3
	s_add_u32 s12, s26, s0
	v_readlane_b32 s28, v254, 4
	s_addc_u32 s13, s27, s1
	v_readlane_b32 s29, v254, 5
	s_add_u32 s38, s28, s0
	v_readlane_b32 s0, v254, 40
	s_addc_u32 s39, s29, s1
	s_add_i32 s0, s0, -14
	s_cmp_lt_u32 s0, 13
	s_cselect_b64 s[0:1], -1, 0
	s_and_b64 s[0:1], s[0:1], s[6:7]
	s_mul_i32 s15, s94, 24
	s_xor_b64 s[8:9], s[0:1], -1
	s_add_i32 s0, s36, s15
	s_cmpk_gt_i32 s0, 0x7fff
	v_cmp_eq_u32_e32 vcc, 0, v162
	s_waitcnt vmcnt(0)
	v_lshlrev_b32_e32 v6, 4, v162
	s_mov_b32 s4, s36
	v_readlane_b32 s17, v253, 57
	v_readlane_b32 s18, v253, 58
	v_readlane_b32 s19, v253, 59
	v_readlane_b32 s20, v253, 60
	v_readlane_b32 s21, v253, 61
	v_readlane_b32 s22, v253, 62
	v_readlane_b32 s23, v253, 63
	v_readlane_b32 s24, v254, 0
	v_readlane_b32 s25, v254, 1
	v_readlane_b32 s30, v254, 6
	v_readlane_b32 s31, v254, 7
	s_cbranch_scc1 .LBB0_703
	v_readlane_b32 s0, v254, 43
	v_readlane_b32 s1, v254, 44
	s_add_u32 s56, s0, 0x40000
	v_lshlrev_b32_e32 v2, 3, v162
	v_mov_b32_e32 v3, v0
	s_addc_u32 s57, s1, 0
	v_lshl_add_u64 v[4:5], s[0:1], 0, v[2:3]
	s_mov_b64 s[0:1], 0x1b200000
	v_and_b32_e32 v1, 64, v231
	v_lshl_add_u64 v[8:9], v[4:5], 0, s[0:1]
	v_add_u32_e32 v4, 64, v1
	v_xor_b32_e32 v1, 1, v231
	v_cmp_lt_i32_e64 s[0:1], v1, v4
	v_xor_b32_e32 v5, 2, v231
	v_readlane_b32 s16, v253, 56
	v_cndmask_b32_e64 v1, v231, v1, s[0:1]
	v_cmp_lt_i32_e64 s[0:1], v5, v4
	v_mov_b32_e32 v7, v0
	v_readlane_b32 s30, v254, 6
	v_cndmask_b32_e64 v5, v231, v5, s[0:1]
	v_lshlrev_b32_e32 v86, 2, v5
	v_xor_b32_e32 v5, 4, v231
	v_cmp_lt_i32_e64 s[0:1], v5, v4
	v_readlane_b32 s31, v254, 7
	v_lshlrev_b32_e32 v1, 2, v1
	v_cndmask_b32_e64 v5, v231, v5, s[0:1]
	v_lshlrev_b32_e32 v87, 2, v5
	v_xor_b32_e32 v5, 8, v231
	v_cmp_lt_i32_e64 s[0:1], v5, v4
	s_and_b64 s[40:41], s[8:9], vcc
	v_lshl_add_u64 v[10:11], s[34:35], 0, v[2:3]
	v_cndmask_b32_e64 v5, v231, v5, s[0:1]
	v_lshlrev_b32_e32 v88, 2, v5
	v_xor_b32_e32 v5, 16, v231
	v_cmp_lt_i32_e64 s[0:1], v5, v4
	v_lshl_add_u64 v[12:13], s[12:13], 0, v[6:7]
	v_lshl_add_u64 v[14:15], s[38:39], 0, v[6:7]
	v_cndmask_b32_e64 v5, v231, v5, s[0:1]
	v_lshlrev_b32_e32 v89, 2, v5
	v_xor_b32_e32 v5, 32, v231
	v_cmp_lt_i32_e64 s[0:1], v5, v4
	v_lshl_add_u64 v[16:17], s[30:31], 0, v[6:7]
	s_lshl_b32 s58, s94, 4
	v_cndmask_b32_e64 v4, v231, v5, s[0:1]
	v_lshlrev_b32_e32 v90, 2, v4
	s_mov_b32 s4, s36
	s_mov_b32 s2, 0xf800000
	v_readlane_b32 s17, v253, 57
	v_readlane_b32 s18, v253, 58
	v_readlane_b32 s19, v253, 59
	v_readlane_b32 s20, v253, 60
	v_readlane_b32 s21, v253, 61
	v_readlane_b32 s22, v253, 62
	v_readlane_b32 s23, v253, 63
	v_readlane_b32 s24, v254, 0
	v_readlane_b32 s25, v254, 1
	v_readlane_b32 s26, v254, 2
	v_readlane_b32 s27, v254, 3
	v_readlane_b32 s28, v254, 4
	v_readlane_b32 s29, v254, 5
	global_load_dwordx4 v[116:119], v[12:13], off
	global_load_dwordx4 v[120:123], v[12:13], off offset:1024
	global_load_dwordx4 v[124:127], v[12:13], off offset:2048
	global_load_dwordx4 v[128:131], v[12:13], off offset:3072
	global_load_dwordx4 v[132:135], v[14:15], off
	global_load_dwordx4 v[136:139], v[14:15], off offset:1024
	global_load_dwordx4 v[140:143], v[14:15], off offset:2048
	global_load_dwordx4 v[144:147], v[14:15], off offset:3072
	s_mov_b32 s100, 0
	s_branch .LBB0_631

; template <int NR>
; __device__ __forceinline__ void ln_rows(const _Float16* z, bf16* xb, float* st, float* outf, int m0, int stride, const float* g, const float* b, int lane, bool final_out) {
;     ...
;     for (int r = 0; r < NR; ++r) { const h16x4* zr = (const h16x4*)(z + (size_t)(m0 + r * stride) * D) + lane; s[r] = 0.f;
; #pragma unroll
;         for (int j = 0; j < 4; ++j) v[r][j] = __builtin_convertvector(zr[64 * j], f32x4); }
; #pragma unroll
;     for (int r = 0; r < NR; ++r)
; #pragma unroll
;         for (int j = 0; j < 4; ++j) s[r] += (v[r][j].x + v[r][j].y) + (v[r][j].z + v[r][j].w);
; __global__ void __launch_bounds__(NTHR, 2) fwd_kernel(Params p) {
;     ...
;             { int m = gw;
;               for (; m + 3 * ngw < T; m += 4 * ngw) ln_rows<4>((const _Float16*)(ws_ + WS_Z16), XB, (float*)(ws_ + WS_STATS), p.out, m, ngw, gg, bb, lane, !wbf);
.LBB0_631:
	s_ashr_i32 s5, s4, 31
	s_lshl_b64 s[54:55], s[4:5], 11
	s_add_i32 s42, s4, s14
	s_ashr_i32 s43, s42, 31
	s_lshl_b64 s[52:53], s[42:43], 11
	s_add_i32 s48, s58, s4
	s_ashr_i32 s49, s48, 31
	s_lshl_b64 s[50:51], s[48:49], 11
	s_add_i32 s44, s15, s4
	s_ashr_i32 s45, s44, 31
	s_lshl_b64 s[46:47], s[44:45], 11
	s_cmp_eq_u32 s100, 0
	s_cbranch_scc1 .Lln_load
	s_waitcnt vmcnt(0)
	v_mov_b64_e32 v[44:45], v[198:199]
	v_mov_b64_e32 v[42:43], v[200:201]
	v_mov_b64_e32 v[40:41], v[202:203]
	v_mov_b64_e32 v[38:39], v[204:205]
	v_mov_b64_e32 v[36:37], v[206:207]
	v_mov_b64_e32 v[34:35], v[208:209]
	v_mov_b64_e32 v[32:33], v[210:211]
	v_mov_b64_e32 v[30:31], v[212:213]
	v_mov_b64_e32 v[28:29], v[214:215]
	v_mov_b64_e32 v[26:27], v[216:217]
	v_mov_b64_e32 v[24:25], v[218:219]
	v_mov_b64_e32 v[22:23], v[220:221]
	v_mov_b64_e32 v[20:21], v[222:223]
	v_mov_b64_e32 v[18:19], v[224:225]
	v_mov_b64_e32 v[4:5], v[226:227]
	v_mov_b64_e32 v[2:3], v[228:229]
	s_branch .Lln_join
.Lln_load:
	v_lshl_add_u64 v[2:3], v[8:9], 0, s[54:55]
	flat_load_dwordx2 v[44:45], v[2:3]
	flat_load_dwordx2 v[42:43], v[2:3] offset:512
	flat_load_dwordx2 v[40:41], v[2:3] offset:1024
	flat_load_dwordx2 v[38:39], v[2:3] offset:1536
	v_lshl_add_u64 v[2:3], v[8:9], 0, s[52:53]
	flat_load_dwordx2 v[36:37], v[2:3]
	flat_load_dwordx2 v[34:35], v[2:3] offset:512
	flat_load_dwordx2 v[32:33], v[2:3] offset:1024
	flat_load_dwordx2 v[30:31], v[2:3] offset:1536
	v_lshl_add_u64 v[2:3], v[8:9], 0, s[50:51]
	flat_load_dwordx2 v[28:29], v[2:3]
	flat_load_dwordx2 v[26:27], v[2:3] offset:512
	flat_load_dwordx2 v[24:25], v[2:3] offset:1024
	flat_load_dwordx2 v[22:23], v[2:3] offset:1536
	v_lshl_add_u64 v[2:3], v[8:9], 0, s[46:47]
	flat_load_dwordx2 v[20:21], v[2:3]
	flat_load_dwordx2 v[18:19], v[2:3] offset:512
	flat_load_dwordx2 v[4:5], v[2:3] offset:1024
	flat_load_dwordx2 v[2:3], v[2:3] offset:1536
.Lln_join:
	s_waitcnt vmcnt(0) lgkmcnt(0)
	s_lshl_b32 s0, s14, 2
	s_add_i32 s0, s0, s4
	s_add_i32 s1, s0, s15
	s_mov_b32 s100, 0
	s_cmpk_gt_i32 s1, 0x7fff
	s_cbranch_scc1 .Lln_nopf
	s_ashr_i32 s1, s0, 31
	s_lshl_b64 s[98:99], s[0:1], 11
	v_lshl_add_u64 v[246:247], v[8:9], 0, s[98:99]
	global_load_dwordx2 v[198:199], v[246:247], off
	global_load_dwordx2 v[200:201], v[246:247], off offset:512
	global_load_dwordx2 v[202:203], v[246:247], off offset:1024
	global_load_dwordx2 v[204:205], v[246:247], off offset:1536
	s_add_i32 s0, s0, s14
	s_ashr_i32 s1, s0, 31
	s_lshl_b64 s[98:99], s[0:1], 11
	v_lshl_add_u64 v[246:247], v[8:9], 0, s[98:99]
	global_load_dwordx2 v[206:207], v[246:247], off
	global_load_dwordx2 v[208:209], v[246:247], off offset:512
	global_load_dwordx2 v[210:211], v[246:247], off offset:1024
	global_load_dwordx2 v[212:213], v[246:247], off offset:1536
	s_add_i32 s0, s0, s14
	s_ashr_i32 s1, s0, 31
	s_lshl_b64 s[98:99], s[0:1], 11
	v_lshl_add_u64 v[246:247], v[8:9], 0, s[98:99]
	global_load_dwordx2 v[214:215], v[246:247], off
	global_load_dwordx2 v[216:217], v[246:247], off offset:512
	global_load_dwordx2 v[218:219], v[246:247], off offset:1024
	global_load_dwordx2 v[220:221], v[246:247], off offset:1536
	s_add_i32 s0, s0, s14
	s_ashr_i32 s1, s0, 31
	s_lshl_b64 s[98:99], s[0:1], 11
	v_lshl_add_u64 v[246:247], v[8:9], 0, s[98:99]
	global_load_dwordx2 v[222:223], v[246:247], off
	global_load_dwordx2 v[224:225], v[246:247], off offset:512
	global_load_dwordx2 v[226:227], v[246:247], off offset:1024
	global_load_dwordx2 v[228:229], v[246:247], off offset:1536
	s_mov_b32 s100, 1
.Lln_nopf:
	v_cvt_f32_f16_e32 v46, v44
	v_cvt_f32_f16_sdwa v47, v45 dst_sel:DWORD dst_unused:UNUSED_PAD src0_sel:WORD_1
	v_cvt_f32_f16_e32 v49, v45
	v_cvt_f32_f16_sdwa v48, v44 dst_sel:DWORD dst_unused:UNUSED_PAD src0_sel:WORD_1
	v_cvt_f32_f16_e32 v50, v42
	v_cvt_f32_f16_sdwa v51, v43 dst_sel:DWORD dst_unused:UNUSED_PAD src0_sel:WORD_1
	v_cvt_f32_f16_e32 v53, v43
	v_cvt_f32_f16_sdwa v52, v42 dst_sel:DWORD dst_unused:UNUSED_PAD src0_sel:WORD_1
	v_cvt_f32_f16_e32 v7, v41
	v_cvt_f32_f16_sdwa v54, v41 dst_sel:DWORD dst_unused:UNUSED_PAD src0_sel:WORD_1
	v_cvt_f32_f16_e32 v56, v40
	v_cvt_f32_f16_sdwa v68, v40 dst_sel:DWORD dst_unused:UNUSED_PAD src0_sel:WORD_1
	v_cvt_f32_f16_sdwa v70, v38 dst_sel:DWORD dst_unused:UNUSED_PAD src0_sel:WORD_1
	v_pk_add_f32 v[46:47], v[48:49], v[46:47]
	v_cvt_f32_f16_sdwa v55, v39 dst_sel:DWORD dst_unused:UNUSED_PAD src0_sel:WORD_1
	v_cvt_f32_f16_e32 v57, v39
	v_cvt_f32_f16_e32 v59, v38
	v_add_f32_e32 v46, v46, v47
	v_add_f32_e32 v58, 0, v46
	v_pk_add_f32 v[46:47], v[52:53], v[50:51]
	v_cvt_f32_f16_e32 v60, v36
	v_cvt_f32_f16_sdwa v61, v37 dst_sel:DWORD dst_unused:UNUSED_PAD src0_sel:WORD_1
	v_cvt_f32_f16_e32 v63, v37
	v_cvt_f32_f16_sdwa v62, v36 dst_sel:DWORD dst_unused:UNUSED_PAD src0_sel:WORD_1
	v_pk_add_f32 v[46:47], v[46:47], v[46:47] op_sel:[0,1] op_sel_hi:[1,0]
	v_add_f32_e32 v56, v56, v68
	v_add_f32_e32 v54, v7, v54
	v_mov_b32_e32 v47, v70
	v_cvt_f32_f16_e32 v64, v34
	v_cvt_f32_f16_sdwa v65, v35 dst_sel:DWORD dst_unused:UNUSED_PAD src0_sel:WORD_1
	v_cvt_f32_f16_e32 v67, v35
	v_cvt_f32_f16_sdwa v66, v34 dst_sel:DWORD dst_unused:UNUSED_PAD src0_sel:WORD_1
	v_pk_add_f32 v[46:47], v[58:59], v[46:47]
	v_pk_add_f32 v[48:49], v[56:57], v[54:55]
	v_cvt_f32_f16_e32 v82, v33
	v_pk_add_f32 v[46:47], v[46:47], v[48:49]
	v_cvt_f32_f16_sdwa v84, v33 dst_sel:DWORD dst_unused:UNUSED_PAD src0_sel:WORD_1
	v_cvt_f32_f16_e32 v91, v32
	v_cvt_f32_f16_sdwa v92, v32 dst_sel:DWORD dst_unused:UNUSED_PAD src0_sel:WORD_1
	v_cvt_f32_f16_sdwa v102, v30 dst_sel:DWORD dst_unused:UNUSED_PAD src0_sel:WORD_1
	v_add_f32_e32 v7, v46, v47
	v_pk_add_f32 v[46:47], v[62:63], v[60:61]
; template <int NR>
; __device__ __forceinline__ void ln_rows(const _Float16* z, bf16* xb, float* st, float* outf, int m0, int stride, const float* g, const float* b, int lane, bool final_out) {
;     ...
;     for (int r = 0; r < NR; ++r)
; #pragma unroll
;         for (int j = 0; j < 4; ++j) s[r] += (v[r][j].x + v[r][j].y) + (v[r][j].z + v[r][j].w);
; #pragma unroll
;     for (int o = 1; o < 64; o <<= 1)
; #pragma unroll
;         for (int r = 0; r < NR; ++r) s[r] += __shfl_xor(s[r], o);
	v_cvt_f32_f16_sdwa v69, v31 dst_sel:DWORD dst_unused:UNUSED_PAD src0_sel:WORD_1
	v_cvt_f32_f16_e32 v71, v31
	v_cvt_f32_f16_e32 v73, v30
	v_add_f32_e32 v46, v46, v47
	v_add_f32_e32 v72, 0, v46
	v_pk_add_f32 v[46:47], v[66:67], v[64:65]
	v_cvt_f32_f16_e32 v74, v28
	v_cvt_f32_f16_sdwa v75, v29 dst_sel:DWORD dst_unused:UNUSED_PAD src0_sel:WORD_1
	v_cvt_f32_f16_e32 v77, v29
	v_cvt_f32_f16_sdwa v76, v28 dst_sel:DWORD dst_unused:UNUSED_PAD src0_sel:WORD_1
	v_pk_add_f32 v[46:47], v[46:47], v[46:47] op_sel:[0,1] op_sel_hi:[1,0]
	v_add_f32_e32 v70, v91, v92
	v_add_f32_e32 v68, v82, v84
	v_mov_b32_e32 v47, v102
	v_cvt_f32_f16_e32 v78, v26
	v_cvt_f32_f16_sdwa v79, v27 dst_sel:DWORD dst_unused:UNUSED_PAD src0_sel:WORD_1
	v_cvt_f32_f16_e32 v81, v27
	v_cvt_f32_f16_sdwa v80, v26 dst_sel:DWORD dst_unused:UNUSED_PAD src0_sel:WORD_1
	v_pk_add_f32 v[46:47], v[72:73], v[46:47]
	v_pk_add_f32 v[48:49], v[70:71], v[68:69]
	v_cvt_f32_f16_e32 v104, v25
	v_pk_add_f32 v[46:47], v[46:47], v[48:49]
	v_cvt_f32_f16_sdwa v106, v25 dst_sel:DWORD dst_unused:UNUSED_PAD src0_sel:WORD_1
	v_cvt_f32_f16_e32 v108, v24
	v_cvt_f32_f16_sdwa v109, v24 dst_sel:DWORD dst_unused:UNUSED_PAD src0_sel:WORD_1
	v_cvt_f32_f16_sdwa v110, v22 dst_sel:DWORD dst_unused:UNUSED_PAD src0_sel:WORD_1
	v_add_f32_e32 v50, v46, v47
	v_pk_add_f32 v[46:47], v[76:77], v[74:75]
	v_cvt_f32_f16_sdwa v83, v23 dst_sel:DWORD dst_unused:UNUSED_PAD src0_sel:WORD_1
	v_cvt_f32_f16_e32 v85, v23
	v_cvt_f32_f16_e32 v93, v22
	v_add_f32_e32 v46, v46, v47
	v_add_f32_e32 v92, 0, v46
	v_pk_add_f32 v[46:47], v[80:81], v[78:79]
	v_cvt_f32_f16_e32 v94, v20
	v_cvt_f32_f16_sdwa v95, v21 dst_sel:DWORD dst_unused:UNUSED_PAD src0_sel:WORD_1
	v_cvt_f32_f16_e32 v97, v21
	v_cvt_f32_f16_sdwa v96, v20 dst_sel:DWORD dst_unused:UNUSED_PAD src0_sel:WORD_1
	v_pk_add_f32 v[46:47], v[46:47], v[46:47] op_sel:[0,1] op_sel_hi:[1,0]
	v_add_f32_e32 v84, v108, v109
	v_add_f32_e32 v82, v104, v106
	v_mov_b32_e32 v47, v110
	v_cvt_f32_f16_e32 v98, v18
	v_cvt_f32_f16_sdwa v99, v19 dst_sel:DWORD dst_unused:UNUSED_PAD src0_sel:WORD_1
	v_cvt_f32_f16_e32 v101, v19
	v_cvt_f32_f16_sdwa v100, v18 dst_sel:DWORD dst_unused:UNUSED_PAD src0_sel:WORD_1
	v_pk_add_f32 v[46:47], v[92:93], v[46:47]
	v_pk_add_f32 v[48:49], v[84:85], v[82:83]
	v_cvt_f32_f16_e32 v111, v5
	v_pk_add_f32 v[46:47], v[46:47], v[48:49]
	v_cvt_f32_f16_sdwa v112, v5 dst_sel:DWORD dst_unused:UNUSED_PAD src0_sel:WORD_1
	v_cvt_f32_f16_e32 v113, v4
	v_cvt_f32_f16_sdwa v114, v4 dst_sel:DWORD dst_unused:UNUSED_PAD src0_sel:WORD_1
	v_cvt_f32_f16_sdwa v115, v2 dst_sel:DWORD dst_unused:UNUSED_PAD src0_sel:WORD_1
	v_add_f32_e32 v51, v46, v47
	v_pk_add_f32 v[46:47], v[96:97], v[94:95]
	v_cvt_f32_f16_sdwa v103, v3 dst_sel:DWORD dst_unused:UNUSED_PAD src0_sel:WORD_1
	v_cvt_f32_f16_e32 v105, v3
	v_cvt_f32_f16_e32 v107, v2
	v_add_f32_e32 v46, v46, v47
	v_add_f32_e32 v106, 0, v46
	v_pk_add_f32 v[46:47], v[100:101], v[98:99]
	v_add_f32_e32 v104, v113, v114
	v_pk_add_f32 v[46:47], v[46:47], v[46:47] op_sel:[0,1] op_sel_hi:[1,0]
	v_add_f32_e32 v102, v111, v112
	v_mov_b32_e32 v47, v115
	v_pk_add_f32 v[46:47], v[106:107], v[46:47]
	v_pk_add_f32 v[48:49], v[104:105], v[102:103]
	s_nop 0
	v_pk_add_f32 v[46:47], v[46:47], v[48:49]
	v_mov_b32_dpp v48, v50 quad_perm:[1,0,3,2] row_mask:0xf bank_mask:0xf
	v_add_f32_e32 v46, v46, v47
	v_mov_b32_dpp v47, v7 quad_perm:[1,0,3,2] row_mask:0xf bank_mask:0xf
	v_mov_b32_dpp v49, v51 quad_perm:[1,0,3,2] row_mask:0xf bank_mask:0xf
	v_mov_b32_dpp v52, v46 quad_perm:[1,0,3,2] row_mask:0xf bank_mask:0xf
	s_waitcnt lgkmcnt(0)
	v_add_f32_e32 v7, v7, v47
	v_add_f32_e32 v47, v50, v48
	s_waitcnt lgkmcnt(0)
	v_add_f32_e32 v48, v51, v49
	v_mov_b32_dpp v49, v7 quad_perm:[2,3,0,1] row_mask:0xf bank_mask:0xf
	v_mov_b32_dpp v50, v47 quad_perm:[2,3,0,1] row_mask:0xf bank_mask:0xf
	v_mov_b32_dpp v51, v48 quad_perm:[2,3,0,1] row_mask:0xf bank_mask:0xf
	s_waitcnt lgkmcnt(0)
	v_add_f32_e32 v46, v46, v52
	s_nop 1
	v_mov_b32_dpp v52, v46 quad_perm:[2,3,0,1] row_mask:0xf bank_mask:0xf
	s_waitcnt lgkmcnt(0)
	v_add_f32_e32 v7, v7, v49
	s_nop 1
	v_mov_b32_dpp v49, v7 row_half_mirror row_mask:0xf bank_mask:0xf
	s_waitcnt lgkmcnt(0)
	v_add_f32_e32 v47, v47, v50
	s_nop 1
	v_mov_b32_dpp v50, v47 row_half_mirror row_mask:0xf bank_mask:0xf
	s_waitcnt lgkmcnt(0)
	v_add_f32_e32 v48, v48, v51
	s_nop 1
	v_mov_b32_dpp v51, v48 row_half_mirror row_mask:0xf bank_mask:0xf
	s_waitcnt lgkmcnt(0)
	v_add_f32_e32 v46, v46, v52
	s_waitcnt lgkmcnt(0)
	v_add_f32_e32 v7, v7, v49
	v_mov_b32_dpp v52, v46 row_half_mirror row_mask:0xf bank_mask:0xf
	s_nop 0
	v_mov_b32_dpp v49, v7 row_mirror row_mask:0xf bank_mask:0xf
	s_waitcnt lgkmcnt(0)
	v_add_f32_e32 v47, v47, v50
	s_nop 1
	v_mov_b32_dpp v50, v47 row_mirror row_mask:0xf bank_mask:0xf
	s_waitcnt lgkmcnt(0)
	v_add_f32_e32 v48, v48, v51
	s_nop 1
	v_mov_b32_dpp v51, v48 row_mirror row_mask:0xf bank_mask:0xf
	s_waitcnt lgkmcnt(0)
	v_add_f32_e32 v46, v46, v52
	s_waitcnt lgkmcnt(0)
	v_add_f32_e32 v7, v7, v49
	v_mov_b32_dpp v52, v46 row_mirror row_mask:0xf bank_mask:0xf
	ds_bpermute_b32 v49, v89, v7
	s_waitcnt lgkmcnt(0)
	v_add_f32_e32 v47, v47, v50
	ds_bpermute_b32 v50, v89, v47
	s_waitcnt lgkmcnt(0)
	v_add_f32_e32 v48, v48, v51
	ds_bpermute_b32 v51, v89, v48
	s_waitcnt lgkmcnt(0)
	v_add_f32_e32 v46, v46, v52
	s_waitcnt lgkmcnt(0)
	v_add_f32_e32 v7, v7, v49
	ds_bpermute_b32 v52, v89, v46
	ds_bpermute_b32 v49, v90, v7
	s_waitcnt lgkmcnt(0)
	v_add_f32_e32 v47, v47, v50
	ds_bpermute_b32 v50, v90, v47
	s_waitcnt lgkmcnt(0)
	v_add_f32_e32 v48, v48, v51
	ds_bpermute_b32 v51, v90, v48
	s_waitcnt lgkmcnt(0)
	v_add_f32_e32 v46, v46, v52
	s_waitcnt lgkmcnt(0)
; template <int NR>
; __device__ __forceinline__ void ln_rows(const _Float16* z, bf16* xb, float* st, float* outf, int m0, int stride, const float* g, const float* b, int lane, bool final_out) {
;     ...
;     float mean[NR], s2[NR];
; #pragma unroll
;     for (int r = 0; r < NR; ++r) { mean[r] = s[r] * (1.f / D); s2[r] = 0.f;
; #pragma unroll
;         for (int j = 0; j < 4; ++j) { v[r][j] = v[r][j] - mean[r]; s2[r] += (v[r][j].x * v[r][j].x + v[r][j].y * v[r][j].y) + (v[r][j].z * v[r][j].z + v[r][j].w * v[r][j].w); } }
	v_add_f32_e32 v82, v7, v49
	ds_bpermute_b32 v52, v90, v46
	v_fma_mix_f32 v79, v82, s92, v45 op_sel:[0,0,1] op_sel_hi:[0,0,1]
	v_fma_mix_f32 v81, v82, s92, v44 op_sel:[0,0,1] op_sel_hi:[0,0,1]
	v_fma_mix_f32 v75, v82, s92, v43 op_sel:[0,0,1] op_sel_hi:[0,0,1]
	v_fma_mix_f32 v77, v82, s92, v42 op_sel:[0,0,1] op_sel_hi:[0,0,1]
	s_waitcnt lgkmcnt(0)
	v_add_f32_e32 v94, v47, v50
	v_fma_mix_f32 v78, v82, s92, v45 op_sel_hi:[0,0,1]
	v_fma_mix_f32 v80, v82, s92, v44 op_sel_hi:[0,0,1]
	v_mul_f32_e32 v44, v81, v81
	v_mul_f32_e32 v45, v79, v79
	v_fma_mix_f32 v74, v82, s92, v43 op_sel_hi:[0,0,1]
	v_fma_mix_f32 v76, v82, s92, v42 op_sel_hi:[0,0,1]
	v_mul_f32_e32 v42, v77, v77
	v_mul_f32_e32 v43, v75, v75
	v_fma_mix_f32 v71, v82, s92, v41 op_sel:[0,0,1] op_sel_hi:[0,0,1]
	v_fma_mix_f32 v73, v82, s92, v40 op_sel:[0,0,1] op_sel_hi:[0,0,1]
	v_fmac_f32_e32 v44, v80, v80
	v_fmac_f32_e32 v45, v78, v78
	v_fmac_f32_e32 v42, v76, v76
	v_fmac_f32_e32 v43, v74, v74
	v_fma_mix_f32 v70, v82, s92, v41 op_sel_hi:[0,0,1]
	v_fma_mix_f32 v72, v82, s92, v40 op_sel_hi:[0,0,1]
	v_mul_f32_e32 v40, v73, v73
	v_mul_f32_e32 v41, v71, v71
	v_fma_mix_f32 v67, v82, s92, v39 op_sel:[0,0,1] op_sel_hi:[0,0,1]
	v_fma_mix_f32 v69, v82, s92, v38 op_sel:[0,0,1] op_sel_hi:[0,0,1]
	v_fma_mix_f32 v63, v94, s92, v37 op_sel:[0,0,1] op_sel_hi:[0,0,1]
	v_fma_mix_f32 v65, v94, s92, v36 op_sel:[0,0,1] op_sel_hi:[0,0,1]
	v_fma_mix_f32 v59, v94, s92, v35 op_sel:[0,0,1] op_sel_hi:[0,0,1]
	v_fma_mix_f32 v61, v94, s92, v34 op_sel:[0,0,1] op_sel_hi:[0,0,1]
	s_waitcnt lgkmcnt(0)
	v_add_f32_e32 v91, v48, v51
	v_add_f32_e32 v44, v44, v45
	v_add_f32_e32 v42, v42, v43
	v_fmac_f32_e32 v40, v72, v72
	v_fmac_f32_e32 v41, v70, v70
	v_fma_mix_f32 v66, v82, s92, v39 op_sel_hi:[0,0,1]
	v_fma_mix_f32 v68, v82, s92, v38 op_sel_hi:[0,0,1]
	v_mul_f32_e32 v38, v69, v69
	v_mul_f32_e32 v39, v67, v67
	v_fma_mix_f32 v62, v94, s92, v37 op_sel_hi:[0,0,1]
	v_fma_mix_f32 v64, v94, s92, v36 op_sel_hi:[0,0,1]
	v_mul_f32_e32 v36, v65, v65
	v_mul_f32_e32 v37, v63, v63
	v_fma_mix_f32 v58, v94, s92, v35 op_sel_hi:[0,0,1]
	v_fma_mix_f32 v60, v94, s92, v34 op_sel_hi:[0,0,1]
	v_mul_f32_e32 v34, v61, v61
	v_mul_f32_e32 v35, v59, v59
	v_fma_mix_f32 v55, v94, s92, v33 op_sel:[0,0,1] op_sel_hi:[0,0,1]
	v_fma_mix_f32 v57, v94, s92, v32 op_sel:[0,0,1] op_sel_hi:[0,0,1]
	v_add_f32_e32 v42, v44, v42
	v_add_f32_e32 v40, v40, v41
	v_fmac_f32_e32 v38, v68, v68
	v_fmac_f32_e32 v39, v66, v66
	v_fmac_f32_e32 v36, v64, v64
	v_fmac_f32_e32 v37, v62, v62
	v_fmac_f32_e32 v34, v60, v60
	v_fmac_f32_e32 v35, v58, v58
	v_fma_mix_f32 v54, v94, s92, v33 op_sel_hi:[0,0,1]
	v_fma_mix_f32 v56, v94, s92, v32 op_sel_hi:[0,0,1]
	v_mul_f32_e32 v32, v57, v57
	v_mul_f32_e32 v33, v55, v55
	v_fma_mix_f32 v47, v91, s92, v29 op_sel:[0,0,1] op_sel_hi:[0,0,1]
	v_fma_mix_f32 v49, v91, s92, v28 op_sel:[0,0,1] op_sel_hi:[0,0,1]
	v_fma_mix_f32 v43, v91, s92, v27 op_sel:[0,0,1] op_sel_hi:[0,0,1]
	v_fma_mix_f32 v45, v91, s92, v26 op_sel:[0,0,1] op_sel_hi:[0,0,1]
	s_waitcnt lgkmcnt(0)
	v_add_f32_e32 v7, v46, v52
	v_add_f32_e32 v40, v40, v42
	v_add_f32_e32 v38, v38, v39
	v_add_f32_e32 v36, v36, v37
	v_add_f32_e32 v34, v34, v35
	v_fmac_f32_e32 v32, v56, v56
	v_fmac_f32_e32 v33, v54, v54
	v_fma_mix_f32 v46, v91, s92, v29 op_sel_hi:[0,0,1]
	v_fma_mix_f32 v48, v91, s92, v28 op_sel_hi:[0,0,1]
	v_mul_f32_e32 v28, v49, v49
	v_mul_f32_e32 v29, v47, v47
	v_fma_mix_f32 v42, v91, s92, v27 op_sel_hi:[0,0,1]
	v_fma_mix_f32 v44, v91, s92, v26 op_sel_hi:[0,0,1]
	v_mul_f32_e32 v26, v45, v45
	v_mul_f32_e32 v27, v43, v43
	v_fma_mix_f32 v39, v91, s92, v25 op_sel:[0,0,1] op_sel_hi:[0,0,1]
	v_fma_mix_f32 v41, v91, s92, v24 op_sel:[0,0,1] op_sel_hi:[0,0,1]
	v_add_f32_e32 v83, v38, v40
	v_add_f32_e32 v34, v36, v34
	v_add_f32_e32 v32, v32, v33
	v_fmac_f32_e32 v28, v48, v48
	v_fmac_f32_e32 v29, v46, v46
	v_fmac_f32_e32 v26, v44, v44
	v_fmac_f32_e32 v27, v42, v42
	v_fma_mix_f32 v38, v91, s92, v25 op_sel_hi:[0,0,1]
	v_fma_mix_f32 v40, v91, s92, v24 op_sel_hi:[0,0,1]
	v_mul_f32_e32 v24, v41, v41
	v_mul_f32_e32 v25, v39, v39
	v_fma_mix_f32 v35, v91, s92, v23 op_sel:[0,0,1] op_sel_hi:[0,0,1]
	v_fma_mix_f32 v37, v91, s92, v22 op_sel:[0,0,1] op_sel_hi:[0,0,1]
	v_add_f32_e32 v32, v32, v34
	v_fma_mix_f32 v51, v94, s92, v31 op_sel:[0,0,1] op_sel_hi:[0,0,1]
	v_fma_mix_f32 v53, v94, s92, v30 op_sel:[0,0,1] op_sel_hi:[0,0,1]
	v_add_f32_e32 v28, v28, v29
	v_add_f32_e32 v26, v26, v27
	v_fmac_f32_e32 v24, v40, v40
	v_fmac_f32_e32 v25, v38, v38
	v_fma_mix_f32 v34, v91, s92, v23 op_sel_hi:[0,0,1]
	v_fma_mix_f32 v36, v91, s92, v22 op_sel_hi:[0,0,1]
	v_mul_f32_e32 v22, v37, v37
	v_mul_f32_e32 v23, v35, v35
	v_fma_mix_f32 v50, v94, s92, v31 op_sel_hi:[0,0,1]
	v_fma_mix_f32 v52, v94, s92, v30 op_sel_hi:[0,0,1]
	v_mul_f32_e32 v30, v53, v53
	v_mul_f32_e32 v31, v51, v51
	v_add_f32_e32 v26, v28, v26
	v_add_f32_e32 v24, v24, v25
	v_fmac_f32_e32 v22, v36, v36
	v_fmac_f32_e32 v23, v34, v34
	v_fmac_f32_e32 v30, v52, v52
	v_fmac_f32_e32 v31, v50, v50
	v_add_f32_e32 v24, v24, v26
	v_add_f32_e32 v22, v22, v23
	v_fma_mix_f32 v23, v7, s92, v5 op_sel:[0,0,1] op_sel_hi:[0,0,1]
	v_fma_mix_f32 v25, v7, s92, v4 op_sel:[0,0,1] op_sel_hi:[0,0,1]
	v_add_f32_e32 v30, v30, v31
	v_add_f32_e32 v85, v22, v24
	v_fma_mix_f32 v31, v7, s92, v21 op_sel:[0,0,1] op_sel_hi:[0,0,1]
	v_fma_mix_f32 v33, v7, s92, v20 op_sel:[0,0,1] op_sel_hi:[0,0,1]
	v_fma_mix_f32 v27, v7, s92, v19 op_sel:[0,0,1] op_sel_hi:[0,0,1]
	v_fma_mix_f32 v29, v7, s92, v18 op_sel:[0,0,1] op_sel_hi:[0,0,1]
	v_fma_mix_f32 v22, v7, s92, v5 op_sel_hi:[0,0,1]
	v_fma_mix_f32 v24, v7, s92, v4 op_sel_hi:[0,0,1]
	v_mul_f32_e32 v4, v25, v25
	v_mul_f32_e32 v5, v23, v23
	v_add_f32_e32 v84, v30, v32
	v_fma_mix_f32 v30, v7, s92, v21 op_sel_hi:[0,0,1]
	v_fma_mix_f32 v32, v7, s92, v20 op_sel_hi:[0,0,1]
	v_mul_f32_e32 v20, v33, v33
	v_mul_f32_e32 v21, v31, v31
	v_fma_mix_f32 v26, v7, s92, v19 op_sel_hi:[0,0,1]
	v_fma_mix_f32 v28, v7, s92, v18 op_sel_hi:[0,0,1]
	v_mul_f32_e32 v18, v29, v29
	v_mul_f32_e32 v19, v27, v27
	v_fmac_f32_e32 v4, v24, v24
	v_fmac_f32_e32 v5, v22, v22
	v_fmac_f32_e32 v20, v32, v32
	v_fmac_f32_e32 v21, v30, v30
	v_fmac_f32_e32 v18, v28, v28
	v_fmac_f32_e32 v19, v26, v26
	v_add_f32_e32 v4, v4, v5
	v_mov_b32_dpp v5, v83 quad_perm:[1,0,3,2] row_mask:0xf bank_mask:0xf
	v_add_f32_e32 v20, v20, v21
	v_add_f32_e32 v18, v18, v19
	v_mov_b32_dpp v92, v84 quad_perm:[1,0,3,2] row_mask:0xf bank_mask:0xf
	v_add_f32_e32 v18, v20, v18
	v_fma_mix_f32 v19, v7, s92, v3 op_sel:[0,0,1] op_sel_hi:[0,0,1]
	v_fma_mix_f32 v21, v7, s92, v2 op_sel:[0,0,1] op_sel_hi:[0,0,1]
	v_add_f32_e32 v4, v4, v18
	v_fma_mix_f32 v18, v7, s92, v3 op_sel_hi:[0,0,1]
	v_fma_mix_f32 v20, v7, s92, v2 op_sel_hi:[0,0,1]
	v_mul_f32_e32 v2, v21, v21
	v_mul_f32_e32 v3, v19, v19
	v_fmac_f32_e32 v2, v20, v20
	v_fmac_f32_e32 v3, v18, v18
	v_add_f32_e32 v2, v2, v3
	s_waitcnt lgkmcnt(0)
; template <int NR>
; __device__ __forceinline__ void ln_rows(const _Float16* z, bf16* xb, float* st, float* outf, int m0, int stride, const float* g, const float* b, int lane, bool final_out) {
;     ...
; #pragma unroll
;     for (int o = 1; o < 64; o <<= 1)
; #pragma unroll
;         for (int r = 0; r < NR; ++r) s2[r] += __shfl_xor(s2[r], o);
; #pragma unroll
;     for (int r = 0; r < NR; ++r) { const int m = m0 + r * stride; const float rstd = 1.f / sqrtf(s2[r] * (1.f / D) + LN_EPS);
;         if (!final_out && lane == 0) *(f32x2*)(st + 2 * (size_t)m) = (f32x2){mean[r], rstd};
	v_add_f32_e32 v3, v83, v5
	v_add_f32_e32 v2, v2, v4
	s_waitcnt lgkmcnt(0)
	v_add_f32_e32 v5, v84, v92
	v_mov_b32_dpp v84, v3 quad_perm:[2,3,0,1] row_mask:0xf bank_mask:0xf
	v_mov_b32_dpp v4, v85 quad_perm:[1,0,3,2] row_mask:0xf bank_mask:0xf
	v_mov_b32_dpp v83, v2 quad_perm:[1,0,3,2] row_mask:0xf bank_mask:0xf
	v_mov_b32_dpp v92, v5 quad_perm:[2,3,0,1] row_mask:0xf bank_mask:0xf
	s_waitcnt lgkmcnt(0)
	v_add_f32_e32 v3, v3, v84
	s_waitcnt lgkmcnt(0)
	v_add_f32_e32 v4, v85, v4
	s_waitcnt lgkmcnt(0)
	v_add_f32_e32 v2, v2, v83
	v_mov_b32_dpp v83, v3 row_half_mirror row_mask:0xf bank_mask:0xf
	v_mov_b32_dpp v85, v4 quad_perm:[2,3,0,1] row_mask:0xf bank_mask:0xf
	s_waitcnt lgkmcnt(0)
	v_add_f32_e32 v5, v5, v92
	v_mov_b32_dpp v84, v2 quad_perm:[2,3,0,1] row_mask:0xf bank_mask:0xf
	s_waitcnt lgkmcnt(0)
	v_add_f32_e32 v3, v3, v83
	s_waitcnt lgkmcnt(0)
	v_add_f32_e32 v4, v4, v85
	v_mov_b32_dpp v83, v3 row_mirror row_mask:0xf bank_mask:0xf
	v_mov_b32_dpp v85, v5 row_half_mirror row_mask:0xf bank_mask:0xf
	v_mov_b32_dpp v92, v4 row_half_mirror row_mask:0xf bank_mask:0xf
	s_waitcnt lgkmcnt(0)
	v_add_f32_e32 v2, v2, v84
	s_nop 1
	v_mov_b32_dpp v84, v2 row_half_mirror row_mask:0xf bank_mask:0xf
	s_waitcnt lgkmcnt(0)
	v_add_f32_e32 v3, v3, v83
	s_waitcnt lgkmcnt(0)
	v_add_f32_e32 v5, v5, v85
	s_waitcnt lgkmcnt(0)
	v_add_f32_e32 v4, v4, v92
	ds_bpermute_b32 v92, v89, v3
	v_mov_b32_dpp v83, v5 row_mirror row_mask:0xf bank_mask:0xf
	s_waitcnt lgkmcnt(0)
	v_add_f32_e32 v2, v2, v84
	s_nop 1
	v_mov_b32_dpp v84, v2 row_mirror row_mask:0xf bank_mask:0xf
	v_mov_b32_dpp v85, v4 row_mirror row_mask:0xf bank_mask:0xf
	s_waitcnt lgkmcnt(0)
	v_add_f32_e32 v3, v3, v92
	s_waitcnt lgkmcnt(0)
	v_add_f32_e32 v5, v5, v83
	ds_bpermute_b32 v83, v90, v3
	s_waitcnt lgkmcnt(0)
	v_add_f32_e32 v2, v2, v84
	s_waitcnt lgkmcnt(0)
	v_add_f32_e32 v4, v4, v85
	ds_bpermute_b32 v92, v89, v2
	ds_bpermute_b32 v85, v89, v4
	s_waitcnt lgkmcnt(0)
	v_add_f32_e32 v3, v3, v83
	v_fmamk_f32 v3, v3, 0x3a800000, v193
	v_mul_f32_e32 v83, 0x4f800000, v3
	v_cmp_gt_f32_e32 vcc, s2, v3
	ds_bpermute_b32 v84, v89, v5
	s_waitcnt lgkmcnt(0)
	v_add_f32_e32 v92, v2, v92
	v_cndmask_b32_e32 v3, v3, v83, vcc
	v_sqrt_f32_e32 v83, v3
	s_waitcnt lgkmcnt(0)
	v_add_f32_e32 v95, v4, v85
	s_waitcnt lgkmcnt(0)
	v_add_f32_e32 v97, v5, v84
	ds_bpermute_b32 v98, v90, v97
	v_add_u32_e32 v2, -1, v83
	v_fma_f32 v4, -v2, v83, v3
	v_cmp_ge_f32_e64 s[0:1], 0, v4
	v_add_u32_e32 v4, 1, v83
	v_fma_f32 v5, -v4, v83, v3
	v_cndmask_b32_e64 v2, v83, v2, s[0:1]
	v_cmp_lt_f32_e64 s[0:1], 0, v5
	ds_bpermute_b32 v96, v90, v95
	ds_bpermute_b32 v93, v90, v92
	v_cndmask_b32_e64 v2, v2, v4, s[0:1]
	v_mul_f32_e32 v4, 0x37800000, v2
	v_cndmask_b32_e32 v2, v2, v4, vcc
	v_cmp_class_f32_e32 vcc, v3, v197
	s_nop 1
	v_cndmask_b32_e32 v2, v2, v3, vcc
	v_div_scale_f32 v3, s[0:1], v2, v2, 1.0
	v_rcp_f32_e32 v4, v3
	s_nop 0
	v_fma_f32 v5, -v3, v4, 1.0
	v_fmac_f32_e32 v4, v5, v4
	v_div_scale_f32 v5, vcc, 1.0, v2, 1.0
	v_mul_f32_e32 v83, v5, v4
	v_fma_f32 v84, -v3, v83, v5
	v_fmac_f32_e32 v83, v84, v4
	v_fma_f32 v3, -v3, v83, v5
	v_div_fmas_f32 v3, v3, v4, v83
	v_div_fixup_f32 v84, v3, v2, 1.0
	s_and_saveexec_b64 s[0:1], s[40:41]
	s_cbranch_execz .LBB0_633
	s_lshl_b64 s[60:61], s[4:5], 3
	s_add_u32 s60, s56, s60
	s_addc_u32 s61, s57, s61
	v_mul_f32_e32 v2, 0x3a800000, v82
	v_mov_b32_e32 v3, v84
	v_mov_b64_e32 v[4:5], s[60:61]
	flat_store_dwordx2 v[4:5], v[2:3]

; __global__ void __launch_bounds__(NTHR, 2) fwd_kernel(Params p) {
	.amdhsa_kernel _Z10fwd_kernel6Params
		.amdhsa_group_segment_fixed_size 0
		.amdhsa_private_segment_fixed_size 0
		.amdhsa_kernarg_size 464
		.amdhsa_user_sgpr_count 2
		.amdhsa_user_sgpr_dispatch_ptr 0
		.amdhsa_user_sgpr_queue_ptr 0
		.amdhsa_user_sgpr_kernarg_segment_ptr 1
		.amdhsa_user_sgpr_dispatch_id 0
		.amdhsa_user_sgpr_kernarg_preload_length 0
		.amdhsa_user_sgpr_kernarg_preload_offset 0
		.amdhsa_user_sgpr_private_segment_size 0
		.amdhsa_uses_dynamic_stack 0
		.amdhsa_enable_private_segment 0
		.amdhsa_system_sgpr_workgroup_id_x 1
		.amdhsa_system_sgpr_workgroup_id_y 0
		.amdhsa_system_sgpr_workgroup_id_z 0
		.amdhsa_system_sgpr_workgroup_info 0
		.amdhsa_system_vgpr_workitem_id 2
		.amdhsa_next_free_vgpr 256
		.amdhsa_next_free_sgpr 102
		.amdhsa_accum_offset 256
		.amdhsa_reserve_vcc 1
		.amdhsa_float_round_mode_32 0
		.amdhsa_float_round_mode_16_64 0
		.amdhsa_float_denorm_mode_32 3
		.amdhsa_float_denorm_mode_16_64 3
		.amdhsa_dx10_clamp 1
		.amdhsa_ieee_mode 1
		.amdhsa_fp16_overflow 0
		.amdhsa_tg_split 0
		.amdhsa_exception_fp_ieee_invalid_op 0
		.amdhsa_exception_fp_denorm_src 0
		.amdhsa_exception_fp_ieee_div_zero 0
		.amdhsa_exception_fp_ieee_overflow 0
		.amdhsa_exception_fp_ieee_underflow 0
		.amdhsa_exception_fp_ieee_inexact 0
		.amdhsa_exception_int_div_zero 0
	.end_amdhsa_kernel
